# stack + barrier leader path: no wait between the early invalidate and the top-counter atomic
# speedup vs baseline: 1.0051x; 1.0051x over previous
.LBB0_461:
	s_andn2_saveexec_b64 s[4:5], s[4:5]
	s_cbranch_execz .LBB0_481
	s_mov_b64 s[4:5], exec
	v_mov_b32_e32 v8, v3
	buffer_inv sc1
	s_waitcnt lgkmcnt(0)
	v_mbcnt_lo_u32_b32 v3, s4, 0
	v_mbcnt_hi_u32_b32 v3, s5, v3
	v_cmp_eq_u32_e32 vcc, 0, v3
	s_and_saveexec_b64 s[6:7], vcc
	s_cbranch_execz .LBB0_464
	s_bcnt1_i32_b64 s4, s[4:5]
	v_mov_b32_e32 v5, s4
	v_readlane_b32 s4, v253, 9
	v_readlane_b32 s5, v253, 10
	s_nop 4
	global_atomic_add v5, v4, v5, s[4:5] sc0

.LBB0_551:
	s_andn2_saveexec_b64 s[6:7], s[6:7]
	s_cbranch_execz .LBB0_571
	s_mov_b64 s[6:7], exec
	v_mov_b32_e32 v8, v3
	buffer_inv sc1
	s_waitcnt lgkmcnt(0)
	v_mbcnt_lo_u32_b32 v3, s6, 0
	v_mbcnt_hi_u32_b32 v3, s7, v3
	v_cmp_eq_u32_e32 vcc, 0, v3
	s_and_saveexec_b64 s[8:9], vcc
	s_cbranch_execz .LBB0_554
	s_bcnt1_i32_b64 s6, s[6:7]
	v_mov_b32_e32 v5, s6
	v_readlane_b32 s6, v253, 9
	v_readlane_b32 s7, v253, 10
	s_nop 4
	global_atomic_add v5, v4, v5, s[6:7] sc0
